# merge epilogue and both out epilogue variants use the LDS-staged transpose (line-major stores/loads); odd XCDs start the out phase half a unit later
# speedup vs baseline: 1.0208x; 1.0126x over previous
; DI bf16x4 pack4(float a, float b, float c, float d) { u32x2v u; u.x = pk2(a, b); u.y = pk2(c, d); return __builtin_bit_cast(bf16x4, u); }
;   DI void operator()(const f32x4 (&acc)[2][2][4][2], const pg8::Unit& u, int wr, int wc, int fr, int fq) const {
;     bf16_t* MERGED = (reinterpret_cast<bf16_t*>(p.ws + OFF_GA));
; #pragma unroll
;     for (int ai = 0; ai < 2; ++ai)
; #pragma unroll
;       for (int m = 0; m < 4; ++m) {
;         const int row = u.pm * 256 + 128 * ai + 64 * wr + 16 * m + fr;
; #pragma unroll
;         for (int bj = 0; bj < 2; ++bj)
; #pragma unroll
;           for (int n = 0; n < 2; ++n) {
;             const size_t idx = (size_t)row * 1024 + u.pn * 256 + 128 * bj + 32 * wc + 16 * n + 4 * fq;
;             const f32x4 a = acc[ai][bj][m][n];
;             if (MODE == 0) {
;               const unsigned g = *reinterpret_cast<const unsigned*>(reinterpret_cast<const unsigned char*>(p.ws + OFF_RB) + idx);
;               const float k = 1.f / 255.f;
;               st4(MERGED + idx, pack4((float)(g & 255u) * k * a[0], (float)((g >> 8) & 255u) * k * a[1], (float)((g >> 16) & 255u) * k * a[2], (float)(g >> 24) * k * a[3]));
.LBB0_2731:
	v_and_b32_e32 v150, 15, v153
	v_and_b32_e32 v151, 63, v153
	v_sub_u32_e32 v148, v148, v150
	v_lshrrev_b32_e32 v151, 2, v151
	v_readlane_b32 s12, v250, 30
	v_readlane_b32 s13, v250, 31
	s_or_b32 s56, s29, s10
	s_mov_b32 s14, 0x3b808081
	v_add_u32_e32 v148, v148, v151
	v_and_b32_e32 v143, 3, v153
	v_lshlrev_b32_e32 v143, 3, v143
	v_add_u32_e32 v149, s56, v143
	v_lshlrev_b32_e32 v149, 1, v149
	v_lshl_add_u32 v149, v148, 11, v149
	v_lshl_add_u32 v143, v148, 5, v143
	v_lshrrev_b32_e32 v141, 6, v153
	v_lshlrev_b32_e32 v141, 11, v141
	v_add_u32_e32 v141, 0x20000, v141
	v_lshl_add_u32 v142, v151, 6, v141
	v_lshl_add_u32 v141, v150, 6, v141
	v_bfe_u32 v150, v153, 4, 2
	v_lshl_add_u32 v141, v150, 4, v141
	v_bfe_u32 v150, v153, 1, 1
	v_lshl_add_u32 v142, v150, 10, v142
	v_and_b32_e32 v150, 1, v153
	v_lshl_add_u32 v142, v150, 5, v142
	s_lshr_b32 s56, s56, 5
	s_mul_i32 s56, s56, 0x204000
	s_add_u32 s64, s48, s56
	s_addc_u32 s65, s49, 0
	s_add_u32 s66, s64, 0x0
	s_addc_u32 s67, s65, 0
	s_add_u32 s68, s64, 0x1000
	s_addc_u32 s69, s65, 0
	s_add_u32 s70, s64, 0x810000
	s_addc_u32 s71, s65, 0
	s_add_u32 s72, s64, 0x811000
	s_addc_u32 s73, s65, 0
	s_nop 1
	global_load_dwordx2 v[204:205], v143, s[66:67]
	global_load_dwordx2 v[206:207], v143, s[70:71]
	global_load_dwordx2 v[208:209], v143, s[66:67] offset:512
	global_load_dwordx2 v[210:211], v143, s[70:71] offset:512
	global_load_dwordx2 v[212:213], v143, s[66:67] offset:1024
	global_load_dwordx2 v[214:215], v143, s[70:71] offset:1024
	global_load_dwordx2 v[216:217], v143, s[66:67] offset:1536
	global_load_dwordx2 v[218:219], v143, s[70:71] offset:1536
	global_load_dwordx2 v[220:221], v143, s[68:69]
	global_load_dwordx2 v[222:223], v143, s[72:73]
	global_load_dwordx2 v[224:225], v143, s[68:69] offset:512
	global_load_dwordx2 v[226:227], v143, s[72:73] offset:512
	global_load_dwordx2 v[228:229], v143, s[68:69] offset:1024
	global_load_dwordx2 v[230:231], v143, s[72:73] offset:1024
	global_load_dwordx2 v[232:233], v143, s[68:69] offset:1536
	global_load_dwordx2 v[234:235], v143, s[72:73] offset:1536
	ds_write_b128 v141, v[130:133]
	ds_write_b128 v141, v[126:129] offset:1024
	ds_read_b128 v[186:189], v142
	ds_read_b128 v[190:193], v142 offset:16
	s_add_u32 s60, s12, 0x0
	s_addc_u32 s61, s13, 0
	ds_write_b128 v141, v[122:125]
	ds_write_b128 v141, v[118:121] offset:1024
	ds_read_b128 v[194:197], v142
	ds_read_b128 v[198:201], v142 offset:16
	s_waitcnt lgkmcnt(4)
	s_waitcnt vmcnt(15)
	v_cvt_f32_ubyte0_e32 v172, v204
	v_cvt_f32_ubyte1_e32 v173, v204
	v_cvt_f32_ubyte2_e32 v174, v204
	v_cvt_f32_ubyte3_e32 v175, v204
	v_cvt_f32_ubyte0_e32 v176, v205
	v_cvt_f32_ubyte1_e32 v177, v205
	v_cvt_f32_ubyte2_e32 v178, v205
	v_cvt_f32_ubyte3_e32 v179, v205
	v_pk_mul_f32 v[172:173], v[172:173], s[14:15] op_sel_hi:[1,0]
	v_pk_mul_f32 v[174:175], v[174:175], s[14:15] op_sel_hi:[1,0]
	v_pk_mul_f32 v[176:177], v[176:177], s[14:15] op_sel_hi:[1,0]
	v_pk_mul_f32 v[178:179], v[178:179], s[14:15] op_sel_hi:[1,0]
	v_pk_mul_f32 v[186:187], v[186:187], v[172:173]
	v_pk_mul_f32 v[188:189], v[188:189], v[174:175]
	v_pk_mul_f32 v[190:191], v[190:191], v[176:177]
	v_pk_mul_f32 v[192:193], v[192:193], v[178:179]
	v_cvt_pk_bf16_f32 v162, v186, v187
	v_cvt_pk_bf16_f32 v163, v188, v189
	v_cvt_pk_bf16_f32 v164, v190, v191
	v_cvt_pk_bf16_f32 v165, v192, v193
	global_store_dwordx4 v149, v[162:165], s[60:61]
	ds_write_b128 v141, v[114:117]
	ds_write_b128 v141, v[110:113] offset:1024
	ds_read_b128 v[186:189], v142
	ds_read_b128 v[190:193], v142 offset:16
	s_waitcnt lgkmcnt(4)
	s_waitcnt vmcnt(15)
	v_cvt_f32_ubyte0_e32 v172, v206
	v_cvt_f32_ubyte1_e32 v173, v206
	v_cvt_f32_ubyte2_e32 v174, v206
	v_cvt_f32_ubyte3_e32 v175, v206
	v_cvt_f32_ubyte0_e32 v176, v207
	v_cvt_f32_ubyte1_e32 v177, v207
	v_cvt_f32_ubyte2_e32 v178, v207
	v_cvt_f32_ubyte3_e32 v179, v207
	v_pk_mul_f32 v[172:173], v[172:173], s[14:15] op_sel_hi:[1,0]
	v_pk_mul_f32 v[174:175], v[174:175], s[14:15] op_sel_hi:[1,0]
	v_pk_mul_f32 v[176:177], v[176:177], s[14:15] op_sel_hi:[1,0]
	v_pk_mul_f32 v[178:179], v[178:179], s[14:15] op_sel_hi:[1,0]
	v_pk_mul_f32 v[194:195], v[194:195], v[172:173]
	v_pk_mul_f32 v[196:197], v[196:197], v[174:175]
	v_pk_mul_f32 v[198:199], v[198:199], v[176:177]
	v_pk_mul_f32 v[200:201], v[200:201], v[178:179]
	v_cvt_pk_bf16_f32 v162, v194, v195
	v_cvt_pk_bf16_f32 v163, v196, v197
	v_cvt_pk_bf16_f32 v164, v198, v199
	v_cvt_pk_bf16_f32 v165, v200, v201
	global_store_dwordx4 v149, v[162:165], s[60:61] offset:256
	s_add_u32 s62, s12, 0x8000
	s_addc_u32 s63, s13, 0
	ds_write_b128 v141, v[106:109]
	ds_write_b128 v141, v[102:105] offset:1024
	ds_read_b128 v[194:197], v142
	ds_read_b128 v[198:201], v142 offset:16
	s_waitcnt lgkmcnt(4)
	s_waitcnt vmcnt(15)
	v_cvt_f32_ubyte0_e32 v172, v208
	v_cvt_f32_ubyte1_e32 v173, v208
	v_cvt_f32_ubyte2_e32 v174, v208
	v_cvt_f32_ubyte3_e32 v175, v208
	v_cvt_f32_ubyte0_e32 v176, v209
	v_cvt_f32_ubyte1_e32 v177, v209
	v_cvt_f32_ubyte2_e32 v178, v209
	v_cvt_f32_ubyte3_e32 v179, v209
	v_pk_mul_f32 v[172:173], v[172:173], s[14:15] op_sel_hi:[1,0]
	v_pk_mul_f32 v[174:175], v[174:175], s[14:15] op_sel_hi:[1,0]
	v_pk_mul_f32 v[176:177], v[176:177], s[14:15] op_sel_hi:[1,0]
	v_pk_mul_f32 v[178:179], v[178:179], s[14:15] op_sel_hi:[1,0]
	v_pk_mul_f32 v[186:187], v[186:187], v[172:173]
	v_pk_mul_f32 v[188:189], v[188:189], v[174:175]
	v_pk_mul_f32 v[190:191], v[190:191], v[176:177]
	v_pk_mul_f32 v[192:193], v[192:193], v[178:179]
	v_cvt_pk_bf16_f32 v162, v186, v187
	v_cvt_pk_bf16_f32 v163, v188, v189
	v_cvt_pk_bf16_f32 v164, v190, v191
	v_cvt_pk_bf16_f32 v165, v192, v193
	global_store_dwordx4 v149, v[162:165], s[62:63]
	ds_write_b128 v141, v[98:101]
	ds_write_b128 v141, v[94:97] offset:1024
	ds_read_b128 v[186:189], v142
	ds_read_b128 v[190:193], v142 offset:16
	s_waitcnt lgkmcnt(4)
; DI bf16x4 pack4(float a, float b, float c, float d) { u32x2v u; u.x = pk2(a, b); u.y = pk2(c, d); return __builtin_bit_cast(bf16x4, u); }
;   DI void operator()(const f32x4 (&acc)[2][2][4][2], const pg8::Unit& u, int wr, int wc, int fr, int fq) const {
;     bf16_t* MERGED = (reinterpret_cast<bf16_t*>(p.ws + OFF_GA));
; #pragma unroll
;     for (int ai = 0; ai < 2; ++ai)
; #pragma unroll
;       for (int m = 0; m < 4; ++m) {
;         const int row = u.pm * 256 + 128 * ai + 64 * wr + 16 * m + fr;
; #pragma unroll
;         for (int bj = 0; bj < 2; ++bj)
; #pragma unroll
;           for (int n = 0; n < 2; ++n) {
;             const size_t idx = (size_t)row * 1024 + u.pn * 256 + 128 * bj + 32 * wc + 16 * n + 4 * fq;
;             const f32x4 a = acc[ai][bj][m][n];
;             if (MODE == 0) {
;               const unsigned g = *reinterpret_cast<const unsigned*>(reinterpret_cast<const unsigned char*>(p.ws + OFF_RB) + idx);
;               const float k = 1.f / 255.f;
;               st4(MERGED + idx, pack4((float)(g & 255u) * k * a[0], (float)((g >> 8) & 255u) * k * a[1], (float)((g >> 16) & 255u) * k * a[2], (float)(g >> 24) * k * a[3]));
	s_waitcnt vmcnt(15)
	v_cvt_f32_ubyte0_e32 v172, v210
	v_cvt_f32_ubyte1_e32 v173, v210
	v_cvt_f32_ubyte2_e32 v174, v210
	v_cvt_f32_ubyte3_e32 v175, v210
	v_cvt_f32_ubyte0_e32 v176, v211
	v_cvt_f32_ubyte1_e32 v177, v211
	v_cvt_f32_ubyte2_e32 v178, v211
	v_cvt_f32_ubyte3_e32 v179, v211
	v_pk_mul_f32 v[172:173], v[172:173], s[14:15] op_sel_hi:[1,0]
	v_pk_mul_f32 v[174:175], v[174:175], s[14:15] op_sel_hi:[1,0]
	v_pk_mul_f32 v[176:177], v[176:177], s[14:15] op_sel_hi:[1,0]
	v_pk_mul_f32 v[178:179], v[178:179], s[14:15] op_sel_hi:[1,0]
	v_pk_mul_f32 v[194:195], v[194:195], v[172:173]
	v_pk_mul_f32 v[196:197], v[196:197], v[174:175]
	v_pk_mul_f32 v[198:199], v[198:199], v[176:177]
	v_pk_mul_f32 v[200:201], v[200:201], v[178:179]
	v_cvt_pk_bf16_f32 v162, v194, v195
	v_cvt_pk_bf16_f32 v163, v196, v197
	v_cvt_pk_bf16_f32 v164, v198, v199
	v_cvt_pk_bf16_f32 v165, v200, v201
	global_store_dwordx4 v149, v[162:165], s[62:63] offset:256
	s_add_u32 s60, s12, 0x10000
	s_addc_u32 s61, s13, 0
	ds_write_b128 v141, v[90:93]
	ds_write_b128 v141, v[86:89] offset:1024
	ds_read_b128 v[194:197], v142
	ds_read_b128 v[198:201], v142 offset:16
	s_waitcnt lgkmcnt(4)
	s_waitcnt vmcnt(15)
	v_cvt_f32_ubyte0_e32 v172, v212
	v_cvt_f32_ubyte1_e32 v173, v212
	v_cvt_f32_ubyte2_e32 v174, v212
	v_cvt_f32_ubyte3_e32 v175, v212
	v_cvt_f32_ubyte0_e32 v176, v213
	v_cvt_f32_ubyte1_e32 v177, v213
	v_cvt_f32_ubyte2_e32 v178, v213
	v_cvt_f32_ubyte3_e32 v179, v213
	v_pk_mul_f32 v[172:173], v[172:173], s[14:15] op_sel_hi:[1,0]
	v_pk_mul_f32 v[174:175], v[174:175], s[14:15] op_sel_hi:[1,0]
	v_pk_mul_f32 v[176:177], v[176:177], s[14:15] op_sel_hi:[1,0]
	v_pk_mul_f32 v[178:179], v[178:179], s[14:15] op_sel_hi:[1,0]
	v_pk_mul_f32 v[186:187], v[186:187], v[172:173]
	v_pk_mul_f32 v[188:189], v[188:189], v[174:175]
	v_pk_mul_f32 v[190:191], v[190:191], v[176:177]
	v_pk_mul_f32 v[192:193], v[192:193], v[178:179]
	v_cvt_pk_bf16_f32 v162, v186, v187
	v_cvt_pk_bf16_f32 v163, v188, v189
	v_cvt_pk_bf16_f32 v164, v190, v191
	v_cvt_pk_bf16_f32 v165, v192, v193
	global_store_dwordx4 v149, v[162:165], s[60:61]
	ds_write_b128 v141, v[82:85]
	ds_write_b128 v141, v[78:81] offset:1024
	ds_read_b128 v[186:189], v142
	ds_read_b128 v[190:193], v142 offset:16
	s_waitcnt lgkmcnt(4)
	s_waitcnt vmcnt(15)
	v_cvt_f32_ubyte0_e32 v172, v214
	v_cvt_f32_ubyte1_e32 v173, v214
	v_cvt_f32_ubyte2_e32 v174, v214
	v_cvt_f32_ubyte3_e32 v175, v214
	v_cvt_f32_ubyte0_e32 v176, v215
	v_cvt_f32_ubyte1_e32 v177, v215
	v_cvt_f32_ubyte2_e32 v178, v215
	v_cvt_f32_ubyte3_e32 v179, v215
	v_pk_mul_f32 v[172:173], v[172:173], s[14:15] op_sel_hi:[1,0]
	v_pk_mul_f32 v[174:175], v[174:175], s[14:15] op_sel_hi:[1,0]
	v_pk_mul_f32 v[176:177], v[176:177], s[14:15] op_sel_hi:[1,0]
	v_pk_mul_f32 v[178:179], v[178:179], s[14:15] op_sel_hi:[1,0]
	v_pk_mul_f32 v[194:195], v[194:195], v[172:173]
	v_pk_mul_f32 v[196:197], v[196:197], v[174:175]
	v_pk_mul_f32 v[198:199], v[198:199], v[176:177]
	v_pk_mul_f32 v[200:201], v[200:201], v[178:179]
	v_cvt_pk_bf16_f32 v162, v194, v195
	v_cvt_pk_bf16_f32 v163, v196, v197
	v_cvt_pk_bf16_f32 v164, v198, v199
	v_cvt_pk_bf16_f32 v165, v200, v201
	global_store_dwordx4 v149, v[162:165], s[60:61] offset:256
	s_add_u32 s62, s12, 0x18000
	s_addc_u32 s63, s13, 0
	ds_write_b128 v141, v[74:77]
	ds_write_b128 v141, v[70:73] offset:1024
	ds_read_b128 v[194:197], v142
	ds_read_b128 v[198:201], v142 offset:16
	s_waitcnt lgkmcnt(4)
	s_waitcnt vmcnt(15)
	v_cvt_f32_ubyte0_e32 v172, v216
	v_cvt_f32_ubyte1_e32 v173, v216
	v_cvt_f32_ubyte2_e32 v174, v216
	v_cvt_f32_ubyte3_e32 v175, v216
	v_cvt_f32_ubyte0_e32 v176, v217
	v_cvt_f32_ubyte1_e32 v177, v217
	v_cvt_f32_ubyte2_e32 v178, v217
	v_cvt_f32_ubyte3_e32 v179, v217
	v_pk_mul_f32 v[172:173], v[172:173], s[14:15] op_sel_hi:[1,0]
	v_pk_mul_f32 v[174:175], v[174:175], s[14:15] op_sel_hi:[1,0]
	v_pk_mul_f32 v[176:177], v[176:177], s[14:15] op_sel_hi:[1,0]
	v_pk_mul_f32 v[178:179], v[178:179], s[14:15] op_sel_hi:[1,0]
	v_pk_mul_f32 v[186:187], v[186:187], v[172:173]
	v_pk_mul_f32 v[188:189], v[188:189], v[174:175]
	v_pk_mul_f32 v[190:191], v[190:191], v[176:177]
	v_pk_mul_f32 v[192:193], v[192:193], v[178:179]
	v_cvt_pk_bf16_f32 v162, v186, v187
	v_cvt_pk_bf16_f32 v163, v188, v189
	v_cvt_pk_bf16_f32 v164, v190, v191
	v_cvt_pk_bf16_f32 v165, v192, v193
	global_store_dwordx4 v149, v[162:165], s[62:63]
	ds_write_b128 v141, v[66:69]
	ds_write_b128 v141, v[62:65] offset:1024
	ds_read_b128 v[186:189], v142
	ds_read_b128 v[190:193], v142 offset:16
	s_waitcnt lgkmcnt(4)
	s_waitcnt vmcnt(15)
	v_cvt_f32_ubyte0_e32 v172, v218
	v_cvt_f32_ubyte1_e32 v173, v218
	v_cvt_f32_ubyte2_e32 v174, v218
	v_cvt_f32_ubyte3_e32 v175, v218
	v_cvt_f32_ubyte0_e32 v176, v219
	v_cvt_f32_ubyte1_e32 v177, v219
	v_cvt_f32_ubyte2_e32 v178, v219
	v_cvt_f32_ubyte3_e32 v179, v219
	v_pk_mul_f32 v[172:173], v[172:173], s[14:15] op_sel_hi:[1,0]
	v_pk_mul_f32 v[174:175], v[174:175], s[14:15] op_sel_hi:[1,0]
	v_pk_mul_f32 v[176:177], v[176:177], s[14:15] op_sel_hi:[1,0]
	v_pk_mul_f32 v[178:179], v[178:179], s[14:15] op_sel_hi:[1,0]
	v_pk_mul_f32 v[194:195], v[194:195], v[172:173]
	v_pk_mul_f32 v[196:197], v[196:197], v[174:175]
	v_pk_mul_f32 v[198:199], v[198:199], v[176:177]
	v_pk_mul_f32 v[200:201], v[200:201], v[178:179]
	v_cvt_pk_bf16_f32 v162, v194, v195
	v_cvt_pk_bf16_f32 v163, v196, v197
	v_cvt_pk_bf16_f32 v164, v198, v199
	v_cvt_pk_bf16_f32 v165, v200, v201
	global_store_dwordx4 v149, v[162:165], s[62:63] offset:256
	s_add_u32 s60, s12, 0x40000
	s_addc_u32 s61, s13, 0
	ds_write_b128 v141, v[58:61]
	ds_write_b128 v141, v[54:57] offset:1024
	ds_read_b128 v[194:197], v142
	ds_read_b128 v[198:201], v142 offset:16
	s_waitcnt lgkmcnt(4)
; DI bf16x4 pack4(float a, float b, float c, float d) { u32x2v u; u.x = pk2(a, b); u.y = pk2(c, d); return __builtin_bit_cast(bf16x4, u); }
;   DI void operator()(const f32x4 (&acc)[2][2][4][2], const pg8::Unit& u, int wr, int wc, int fr, int fq) const {
;     bf16_t* MERGED = (reinterpret_cast<bf16_t*>(p.ws + OFF_GA));
; #pragma unroll
;     for (int ai = 0; ai < 2; ++ai)
; #pragma unroll
;       for (int m = 0; m < 4; ++m) {
;         const int row = u.pm * 256 + 128 * ai + 64 * wr + 16 * m + fr;
; #pragma unroll
;         for (int bj = 0; bj < 2; ++bj)
; #pragma unroll
;           for (int n = 0; n < 2; ++n) {
;             const size_t idx = (size_t)row * 1024 + u.pn * 256 + 128 * bj + 32 * wc + 16 * n + 4 * fq;
;             const f32x4 a = acc[ai][bj][m][n];
;             if (MODE == 0) {
;               const unsigned g = *reinterpret_cast<const unsigned*>(reinterpret_cast<const unsigned char*>(p.ws + OFF_RB) + idx);
;               const float k = 1.f / 255.f;
;               st4(MERGED + idx, pack4((float)(g & 255u) * k * a[0], (float)((g >> 8) & 255u) * k * a[1], (float)((g >> 16) & 255u) * k * a[2], (float)(g >> 24) * k * a[3]));
;             } else {
;               f32x4 x = *reinterpret_cast<const f32x4*>(p.out + idx);
;               x = x * ALPHA + a;
;               *reinterpret_cast<f32x4*>(p.out + idx) = x;
;             }
;           }
;       }
;   }
	s_waitcnt vmcnt(15)
	v_cvt_f32_ubyte0_e32 v172, v220
	v_cvt_f32_ubyte1_e32 v173, v220
	v_cvt_f32_ubyte2_e32 v174, v220
	v_cvt_f32_ubyte3_e32 v175, v220
	v_cvt_f32_ubyte0_e32 v176, v221
	v_cvt_f32_ubyte1_e32 v177, v221
	v_cvt_f32_ubyte2_e32 v178, v221
	v_cvt_f32_ubyte3_e32 v179, v221
	v_pk_mul_f32 v[172:173], v[172:173], s[14:15] op_sel_hi:[1,0]
	v_pk_mul_f32 v[174:175], v[174:175], s[14:15] op_sel_hi:[1,0]
	v_pk_mul_f32 v[176:177], v[176:177], s[14:15] op_sel_hi:[1,0]
	v_pk_mul_f32 v[178:179], v[178:179], s[14:15] op_sel_hi:[1,0]
	v_pk_mul_f32 v[186:187], v[186:187], v[172:173]
	v_pk_mul_f32 v[188:189], v[188:189], v[174:175]
	v_pk_mul_f32 v[190:191], v[190:191], v[176:177]
	v_pk_mul_f32 v[192:193], v[192:193], v[178:179]
	v_cvt_pk_bf16_f32 v162, v186, v187
	v_cvt_pk_bf16_f32 v163, v188, v189
	v_cvt_pk_bf16_f32 v164, v190, v191
	v_cvt_pk_bf16_f32 v165, v192, v193
	global_store_dwordx4 v149, v[162:165], s[60:61]
	ds_write_b128 v141, v[50:53]
	ds_write_b128 v141, v[46:49] offset:1024
	ds_read_b128 v[186:189], v142
	ds_read_b128 v[190:193], v142 offset:16
	s_waitcnt lgkmcnt(4)
	s_waitcnt vmcnt(15)
	v_cvt_f32_ubyte0_e32 v172, v222
	v_cvt_f32_ubyte1_e32 v173, v222
	v_cvt_f32_ubyte2_e32 v174, v222
	v_cvt_f32_ubyte3_e32 v175, v222
	v_cvt_f32_ubyte0_e32 v176, v223
	v_cvt_f32_ubyte1_e32 v177, v223
	v_cvt_f32_ubyte2_e32 v178, v223
	v_cvt_f32_ubyte3_e32 v179, v223
	v_pk_mul_f32 v[172:173], v[172:173], s[14:15] op_sel_hi:[1,0]
	v_pk_mul_f32 v[174:175], v[174:175], s[14:15] op_sel_hi:[1,0]
	v_pk_mul_f32 v[176:177], v[176:177], s[14:15] op_sel_hi:[1,0]
	v_pk_mul_f32 v[178:179], v[178:179], s[14:15] op_sel_hi:[1,0]
	v_pk_mul_f32 v[194:195], v[194:195], v[172:173]
	v_pk_mul_f32 v[196:197], v[196:197], v[174:175]
	v_pk_mul_f32 v[198:199], v[198:199], v[176:177]
	v_pk_mul_f32 v[200:201], v[200:201], v[178:179]
	v_cvt_pk_bf16_f32 v162, v194, v195
	v_cvt_pk_bf16_f32 v163, v196, v197
	v_cvt_pk_bf16_f32 v164, v198, v199
	v_cvt_pk_bf16_f32 v165, v200, v201
	global_store_dwordx4 v149, v[162:165], s[60:61] offset:256
	s_add_u32 s62, s12, 0x48000
	s_addc_u32 s63, s13, 0
	ds_write_b128 v141, v[42:45]
	ds_write_b128 v141, v[38:41] offset:1024
	ds_read_b128 v[194:197], v142
	ds_read_b128 v[198:201], v142 offset:16
	s_waitcnt lgkmcnt(4)
	s_waitcnt vmcnt(15)
	v_cvt_f32_ubyte0_e32 v172, v224
	v_cvt_f32_ubyte1_e32 v173, v224
	v_cvt_f32_ubyte2_e32 v174, v224
	v_cvt_f32_ubyte3_e32 v175, v224
	v_cvt_f32_ubyte0_e32 v176, v225
	v_cvt_f32_ubyte1_e32 v177, v225
	v_cvt_f32_ubyte2_e32 v178, v225
	v_cvt_f32_ubyte3_e32 v179, v225
	v_pk_mul_f32 v[172:173], v[172:173], s[14:15] op_sel_hi:[1,0]
	v_pk_mul_f32 v[174:175], v[174:175], s[14:15] op_sel_hi:[1,0]
	v_pk_mul_f32 v[176:177], v[176:177], s[14:15] op_sel_hi:[1,0]
	v_pk_mul_f32 v[178:179], v[178:179], s[14:15] op_sel_hi:[1,0]
	v_pk_mul_f32 v[186:187], v[186:187], v[172:173]
	v_pk_mul_f32 v[188:189], v[188:189], v[174:175]
	v_pk_mul_f32 v[190:191], v[190:191], v[176:177]
	v_pk_mul_f32 v[192:193], v[192:193], v[178:179]
	v_cvt_pk_bf16_f32 v162, v186, v187
	v_cvt_pk_bf16_f32 v163, v188, v189
	v_cvt_pk_bf16_f32 v164, v190, v191
	v_cvt_pk_bf16_f32 v165, v192, v193
	global_store_dwordx4 v149, v[162:165], s[62:63]
	ds_write_b128 v141, v[34:37]
	ds_write_b128 v141, v[30:33] offset:1024
	ds_read_b128 v[186:189], v142
	ds_read_b128 v[190:193], v142 offset:16
	s_waitcnt lgkmcnt(4)
	s_waitcnt vmcnt(15)
	v_cvt_f32_ubyte0_e32 v172, v226
	v_cvt_f32_ubyte1_e32 v173, v226
	v_cvt_f32_ubyte2_e32 v174, v226
	v_cvt_f32_ubyte3_e32 v175, v226
	v_cvt_f32_ubyte0_e32 v176, v227
	v_cvt_f32_ubyte1_e32 v177, v227
	v_cvt_f32_ubyte2_e32 v178, v227
	v_cvt_f32_ubyte3_e32 v179, v227
	v_pk_mul_f32 v[172:173], v[172:173], s[14:15] op_sel_hi:[1,0]
	v_pk_mul_f32 v[174:175], v[174:175], s[14:15] op_sel_hi:[1,0]
	v_pk_mul_f32 v[176:177], v[176:177], s[14:15] op_sel_hi:[1,0]
	v_pk_mul_f32 v[178:179], v[178:179], s[14:15] op_sel_hi:[1,0]
	v_pk_mul_f32 v[194:195], v[194:195], v[172:173]
	v_pk_mul_f32 v[196:197], v[196:197], v[174:175]
	v_pk_mul_f32 v[198:199], v[198:199], v[176:177]
	v_pk_mul_f32 v[200:201], v[200:201], v[178:179]
	v_cvt_pk_bf16_f32 v162, v194, v195
	v_cvt_pk_bf16_f32 v163, v196, v197
	v_cvt_pk_bf16_f32 v164, v198, v199
	v_cvt_pk_bf16_f32 v165, v200, v201
	global_store_dwordx4 v149, v[162:165], s[62:63] offset:256
	s_add_u32 s60, s12, 0x50000
	s_addc_u32 s61, s13, 0
	ds_write_b128 v141, v[26:29]
	ds_write_b128 v141, v[22:25] offset:1024
	ds_read_b128 v[194:197], v142
	ds_read_b128 v[198:201], v142 offset:16
	s_waitcnt lgkmcnt(4)
; DI bf16x4 pack4(float a, float b, float c, float d) { u32x2v u; u.x = pk2(a, b); u.y = pk2(c, d); return __builtin_bit_cast(bf16x4, u); }
;   DI void operator()(const f32x4 (&acc)[2][2][4][2], const pg8::Unit& u, int wr, int wc, int fr, int fq) const {
;     bf16_t* MERGED = (reinterpret_cast<bf16_t*>(p.ws + OFF_GA));
; #pragma unroll
;     for (int ai = 0; ai < 2; ++ai)
; #pragma unroll
;       for (int m = 0; m < 4; ++m) {
;         const int row = u.pm * 256 + 128 * ai + 64 * wr + 16 * m + fr;
; #pragma unroll
;         for (int bj = 0; bj < 2; ++bj)
; #pragma unroll
;           for (int n = 0; n < 2; ++n) {
;             const size_t idx = (size_t)row * 1024 + u.pn * 256 + 128 * bj + 32 * wc + 16 * n + 4 * fq;
;             const f32x4 a = acc[ai][bj][m][n];
;             if (MODE == 0) {
;               const unsigned g = *reinterpret_cast<const unsigned*>(reinterpret_cast<const unsigned char*>(p.ws + OFF_RB) + idx);
;               const float k = 1.f / 255.f;
;               st4(MERGED + idx, pack4((float)(g & 255u) * k * a[0], (float)((g >> 8) & 255u) * k * a[1], (float)((g >> 16) & 255u) * k * a[2], (float)(g >> 24) * k * a[3]));
;             } else {
;               f32x4 x = *reinterpret_cast<const f32x4*>(p.out + idx);
;               x = x * ALPHA + a;
;               *reinterpret_cast<f32x4*>(p.out + idx) = x;
;             }
;           }
;       }
;   }
	s_waitcnt vmcnt(15)
	v_cvt_f32_ubyte0_e32 v172, v228
	v_cvt_f32_ubyte1_e32 v173, v228
	v_cvt_f32_ubyte2_e32 v174, v228
	v_cvt_f32_ubyte3_e32 v175, v228
	v_cvt_f32_ubyte0_e32 v176, v229
	v_cvt_f32_ubyte1_e32 v177, v229
	v_cvt_f32_ubyte2_e32 v178, v229
	v_cvt_f32_ubyte3_e32 v179, v229
	v_pk_mul_f32 v[172:173], v[172:173], s[14:15] op_sel_hi:[1,0]
	v_pk_mul_f32 v[174:175], v[174:175], s[14:15] op_sel_hi:[1,0]
	v_pk_mul_f32 v[176:177], v[176:177], s[14:15] op_sel_hi:[1,0]
	v_pk_mul_f32 v[178:179], v[178:179], s[14:15] op_sel_hi:[1,0]
	v_pk_mul_f32 v[186:187], v[186:187], v[172:173]
	v_pk_mul_f32 v[188:189], v[188:189], v[174:175]
	v_pk_mul_f32 v[190:191], v[190:191], v[176:177]
	v_pk_mul_f32 v[192:193], v[192:193], v[178:179]
	v_cvt_pk_bf16_f32 v162, v186, v187
	v_cvt_pk_bf16_f32 v163, v188, v189
	v_cvt_pk_bf16_f32 v164, v190, v191
	v_cvt_pk_bf16_f32 v165, v192, v193
	global_store_dwordx4 v149, v[162:165], s[60:61]
	ds_write_b128 v141, v[12:15]
	ds_write_b128 v141, v[8:11] offset:1024
	ds_read_b128 v[186:189], v142
	ds_read_b128 v[190:193], v142 offset:16
	s_waitcnt lgkmcnt(4)
	s_waitcnt vmcnt(15)
	v_cvt_f32_ubyte0_e32 v172, v230
	v_cvt_f32_ubyte1_e32 v173, v230
	v_cvt_f32_ubyte2_e32 v174, v230
	v_cvt_f32_ubyte3_e32 v175, v230
	v_cvt_f32_ubyte0_e32 v176, v231
	v_cvt_f32_ubyte1_e32 v177, v231
	v_cvt_f32_ubyte2_e32 v178, v231
	v_cvt_f32_ubyte3_e32 v179, v231
	v_pk_mul_f32 v[172:173], v[172:173], s[14:15] op_sel_hi:[1,0]
	v_pk_mul_f32 v[174:175], v[174:175], s[14:15] op_sel_hi:[1,0]
	v_pk_mul_f32 v[176:177], v[176:177], s[14:15] op_sel_hi:[1,0]
	v_pk_mul_f32 v[178:179], v[178:179], s[14:15] op_sel_hi:[1,0]
	v_pk_mul_f32 v[194:195], v[194:195], v[172:173]
	v_pk_mul_f32 v[196:197], v[196:197], v[174:175]
	v_pk_mul_f32 v[198:199], v[198:199], v[176:177]
	v_pk_mul_f32 v[200:201], v[200:201], v[178:179]
	v_cvt_pk_bf16_f32 v162, v194, v195
	v_cvt_pk_bf16_f32 v163, v196, v197
	v_cvt_pk_bf16_f32 v164, v198, v199
	v_cvt_pk_bf16_f32 v165, v200, v201
	global_store_dwordx4 v149, v[162:165], s[60:61] offset:256
	s_add_u32 s62, s12, 0x58000
	s_addc_u32 s63, s13, 0
	ds_write_b128 v141, v[4:7]
	ds_write_b128 v141, v[0:3] offset:1024
	ds_read_b128 v[194:197], v142
	ds_read_b128 v[198:201], v142 offset:16
	s_waitcnt lgkmcnt(4)
	s_waitcnt vmcnt(15)
	v_cvt_f32_ubyte0_e32 v172, v232
	v_cvt_f32_ubyte1_e32 v173, v232
	v_cvt_f32_ubyte2_e32 v174, v232
	v_cvt_f32_ubyte3_e32 v175, v232
	v_cvt_f32_ubyte0_e32 v176, v233
	v_cvt_f32_ubyte1_e32 v177, v233
	v_cvt_f32_ubyte2_e32 v178, v233
	v_cvt_f32_ubyte3_e32 v179, v233
	v_pk_mul_f32 v[172:173], v[172:173], s[14:15] op_sel_hi:[1,0]
	v_pk_mul_f32 v[174:175], v[174:175], s[14:15] op_sel_hi:[1,0]
	v_pk_mul_f32 v[176:177], v[176:177], s[14:15] op_sel_hi:[1,0]
	v_pk_mul_f32 v[178:179], v[178:179], s[14:15] op_sel_hi:[1,0]
	v_pk_mul_f32 v[186:187], v[186:187], v[172:173]
	v_pk_mul_f32 v[188:189], v[188:189], v[174:175]
	v_pk_mul_f32 v[190:191], v[190:191], v[176:177]
	v_pk_mul_f32 v[192:193], v[192:193], v[178:179]
	v_cvt_pk_bf16_f32 v162, v186, v187
	v_cvt_pk_bf16_f32 v163, v188, v189
	v_cvt_pk_bf16_f32 v164, v190, v191
	v_cvt_pk_bf16_f32 v165, v192, v193
	global_store_dwordx4 v149, v[162:165], s[62:63]
	s_waitcnt lgkmcnt(0)
	s_waitcnt vmcnt(15)
	v_cvt_f32_ubyte0_e32 v172, v234
	v_cvt_f32_ubyte1_e32 v173, v234
	v_cvt_f32_ubyte2_e32 v174, v234
	v_cvt_f32_ubyte3_e32 v175, v234
	v_cvt_f32_ubyte0_e32 v176, v235
	v_cvt_f32_ubyte1_e32 v177, v235
	v_cvt_f32_ubyte2_e32 v178, v235
	v_cvt_f32_ubyte3_e32 v179, v235
	v_pk_mul_f32 v[172:173], v[172:173], s[14:15] op_sel_hi:[1,0]
	v_pk_mul_f32 v[174:175], v[174:175], s[14:15] op_sel_hi:[1,0]
	v_pk_mul_f32 v[176:177], v[176:177], s[14:15] op_sel_hi:[1,0]
	v_pk_mul_f32 v[178:179], v[178:179], s[14:15] op_sel_hi:[1,0]
	v_pk_mul_f32 v[194:195], v[194:195], v[172:173]
	v_pk_mul_f32 v[196:197], v[196:197], v[174:175]
	v_pk_mul_f32 v[198:199], v[198:199], v[176:177]
	v_pk_mul_f32 v[200:201], v[200:201], v[178:179]
	v_cvt_pk_bf16_f32 v162, v194, v195
	v_cvt_pk_bf16_f32 v163, v196, v197
	v_cvt_pk_bf16_f32 v164, v198, v199
	v_cvt_pk_bf16_f32 v165, v200, v201
	global_store_dwordx4 v149, v[162:165], s[62:63] offset:256
	s_mov_b32 s11, s2
	s_mov_b32 s10, s4
	s_mov_b64 s[12:13], s[6:7]
	s_mov_b64 s[14:15], s[8:9]
	s_and_b64 vcc, exec, s[0:1]
	s_cbranch_vccnz .LBB0_2738

; DI int otid() { int t = threadIdx.x; asm volatile("" : "+v"(t)); return t; }
;     DI bool next(int i, Unit& u) const {
;         const long L = (long)i * G + c; if (L >= nwg) return false;
;         int wgid = (int)L; { const int q = nwg / NXCD, r = nwg % NXCD, xcd = wgid % NXCD, off = wgid / NXCD; wgid = (xcd < r ? xcd * (q + 1) : r * (q + 1) + (xcd - r) * q) + off; }
;         const int nig = WGM * nN, gid = wgid / nig, fm = gid * WGM, gsz = (nM - fm) < WGM ? (nM - fm) : WGM;
;         u.pm = fm + ((wgid % nig) % gsz); u.pn = (wgid % nig) / gsz; return true;
;     }
; template <class Epi, class Sched>
; __device__ __forceinline__ void gemm_phase(PG8_LAS unsigned char* lds, const Gemm g, const Sched& S, const Epi& E) {
;     const int tid = otid(), wid = __builtin_amdgcn_readfirstlane(tid >> 6), lane = tid & 63, wr = wid >> 2, wc = wid & 3, fr = lane & 15, fq = lane >> 4;
;     const int K = g.K, nt = K / BK;
;     unsigned voffA[2], voffB[2];
; #pragma unroll
;     for (int i = 0; i < 2; ++i) { int R, C; stage_rc(tid * 16 + i * 8192, R, C); const int Rb = Epi::PERM ? ((R & ~31) + perm32(R & 31)) : R;
;         voffA[i] = (unsigned)(R * K + C) * 2u; voffB[i] = (unsigned)(Rb * K + C) * 2u; }
;     const size_t kstep = (size_t)(BK * 2);
;     const size_t hstep = (size_t)HALF * K * 2;
;     const size_t tstep = 2 * hstep;
;     const unsigned ldsw = (unsigned)wid * 1024u;
;     const int aoff = lds_byte(wr * 64 + fr, fq * 8), boff = lds_byte(wc * 32 + fr, fq * 8);
.LBB0_2747:
	s_or_b64 exec, exec, s[0:1]
	s_mov_b32 s18, 0
	v_writelane_b32 v255, s18, 63
	v_readlane_b32 s18, v249, 6
	v_readlane_b32 s19, v249, 7
	v_mov_b32_e32 v14, v153
	v_readlane_b32 s0, v249, 7
	s_cmp_lt_u32 s0, 16
	s_cbranch_scc1 .Lstg_out_done
	s_bitcmp1_b32 s0, 0
	s_cbranch_scc0 .Lstg_out_done
	s_mov_b32 s0, 8
.Lstg_out_loop:
	s_sleep 127
	s_add_i32 s0, s0, -1
	s_cmp_lg_u32 s0, 0
	s_cbranch_scc1 .Lstg_out_loop
.Lstg_out_done:
.Ltr_o_reenter:
	s_barrier
	s_cmpk_gt_i32 s19, 0x407
	v_readfirstlane_b32 s20, v14
	s_cbranch_scc1 .LBB0_2759
	v_lshlrev_b32_e32 v0, 4, v14
	v_add_u32_e32 v1, 0x2000, v0
	v_ashrrev_i32_e32 v2, 31, v1
	v_lshrrev_b32_e32 v2, 22, v2
	v_add_u32_e32 v2, v1, v2
	v_ashrrev_i32_e32 v8, 10, v2
	v_mul_i32_i24_e32 v3, 0x400, v8
	v_sub_u32_e32 v1, v1, v3
	v_lshrrev_b32_e32 v3, 4, v1
	v_bitop3_b32 v1, v3, v1, 32 bitop3:0x6c
	v_ashrrev_i32_e32 v3, 31, v1
	v_lshrrev_b32_e32 v3, 26, v3
	v_add_u32_e32 v3, v1, v3
	v_ashrrev_i32_e32 v9, 6, v3
	v_and_b32_e32 v3, 0xc0, v3
	v_sub_u32_e32 v1, v1, v3
	v_lshlrev_b32_e32 v2, 5, v8
	v_ashrrev_i16_sdwa v1, v182, sext(v1) dst_sel:DWORD dst_unused:UNUSED_PAD src0_sel:DWORD src1_sel:BYTE_0
	v_and_b32_e32 v2, 32, v2
	v_bfe_i32 v10, v1, 0, 16
	s_ashr_i32 s22, s19, 31
	v_add_u32_e32 v1, v2, v10
	v_lshlrev_b32_e32 v2, 3, v8
	s_lshr_b32 s0, s22, 29
	v_and_b32_e32 v2, 0x1ffff0, v2
	s_add_i32 s0, s19, s0
	s_ashr_i32 s1, s20, 6
	v_add_lshl_u32 v2, v9, v2, 11
	s_ashr_i32 s3, s0, 3
	s_and_b32 s0, s0, -8
	s_ashr_i32 s2, s20, 8
	s_lshl_b32 s21, s1, 10
	v_lshl_add_u32 v18, v1, 1, v2
	v_bfe_i32 v2, v14, 27, 1
	s_sub_i32 s0, s19, s0
	v_lshrrev_b32_e32 v2, 22, v2
	s_cmp_lt_i32 s0, 0
	s_movk_i32 s4, 0x82
	v_add_u32_e32 v2, v0, v2
	s_cselect_b32 s4, s4, 0x81
	v_and_b32_e32 v2, 0xfffffc00, v2
	s_mul_i32 s0, s4, s0
	v_sub_u32_e32 v0, v0, v2
	s_add_i32 s0, s0, s3
	v_lshrrev_b32_e32 v2, 4, v0
	s_ashr_i32 s3, s0, 31
	v_bitop3_b32 v2, v2, v0, 32 bitop3:0x6c
	v_ashrrev_i32_e32 v0, 31, v0
	s_lshr_b32 s3, s3, 27
	v_lshrrev_b32_e32 v0, 26, v0
	s_add_i32 s3, s0, s3
	v_ashrrev_i32_e32 v1, 31, v14
	v_add_u32_e32 v0, v2, v0
	s_ashr_i32 s4, s3, 5
	v_lshrrev_b32_e32 v1, 26, v1
	v_ashrrev_i32_e32 v12, 6, v0
	s_lshl_b32 s6, s4, 3
	v_add_u32_e32 v1, v14, v1
	v_mul_i32_i24_e32 v0, 64, v12
	s_sub_i32 s4, 0x102, s6
	v_ashrrev_i32_e32 v11, 6, v1
	v_sub_u32_e32 v0, v2, v0
	s_min_u32 s7, s4, 8
	s_andn2_b32 s3, s3, 31
	v_lshlrev_b32_e32 v1, 5, v11
	v_ashrrev_i16_sdwa v0, v182, sext(v0) dst_sel:DWORD dst_unused:UNUSED_PAD src0_sel:DWORD src1_sel:BYTE_0
	s_sub_i32 s3, s0, s3
	v_cvt_f32_ubyte0_e32 v3, s7
	v_and_b32_e32 v1, 32, v1
	v_bfe_i32 v13, v0, 0, 16
	v_cvt_f32_i32_e32 v2, s3
	v_rcp_iflag_f32_e32 v4, v3
	v_add_u32_e32 v0, v1, v13
	v_lshlrev_b32_e32 v1, 3, v11
	v_and_b32_e32 v1, 0x1ffff0, v1
	v_add_lshl_u32 v1, v12, v1, 11
	v_lshl_add_u32 v134, v0, 1, v1
	v_mul_f32_e32 v0, v2, v4
	v_trunc_f32_e32 v0, v0
	v_fma_f32 v1, -v0, v3, v2
	v_cvt_i32_f32_e32 v0, v0
	s_ashr_i32 s0, s3, 30
	s_or_b32 s0, s0, 1
	v_cmp_ge_f32_e64 s[4:5], |v1|, v3
	s_and_b64 s[4:5], s[4:5], exec
	s_cselect_b32 s0, s0, 0
	v_readfirstlane_b32 s4, v0
	s_add_i32 s0, s4, s0
	s_mul_i32 s4, s0, s7
	s_sub_i32 s3, s3, s4
	s_sext_i32_i8 s3, s3
	s_add_i32 s10, s6, s3
	s_cmpk_lt_u32 s19, 0x400
	s_cbranch_scc0 .Ltr_o_left
	s_lshr_b32 s0, s19, 3
	s_lshr_b32 s3, s0, 5
	s_sub_u32 s3, 3, s3
	s_lshl_b32 s3, s3, 3
	s_and_b32 s10, s19, 7
	s_add_u32 s10, s10, s3
	s_lshl_b32 s10, s10, 3
	s_and_b32 s3, s0, 7
	s_or_b32 s10, s10, s3
	s_bfe_u32 s0, s0, 0x20003
	s_branch .Ltr_o_join

; DI bf16x4 pack4(float a, float b, float c, float d) { u32x2v u; u.x = pk2(a, b); u.y = pk2(c, d); return __builtin_bit_cast(bf16x4, u); }
;   DI void operator()(const f32x4 (&acc)[2][2][4][2], const pg8::Unit& u, int wr, int wc, int fr, int fq) const {
;     bf16_t* MERGED = (reinterpret_cast<bf16_t*>(p.ws + OFF_GA));
; #pragma unroll
;     for (int ai = 0; ai < 2; ++ai)
; #pragma unroll
;       for (int m = 0; m < 4; ++m) {
;         const int row = u.pm * 256 + 128 * ai + 64 * wr + 16 * m + fr;
; #pragma unroll
;         for (int bj = 0; bj < 2; ++bj)
; #pragma unroll
;           for (int n = 0; n < 2; ++n) {
;             const size_t idx = (size_t)row * 1024 + u.pn * 256 + 128 * bj + 32 * wc + 16 * n + 4 * fq;
;             const f32x4 a = acc[ai][bj][m][n];
;             if (MODE == 0) {
;               const unsigned g = *reinterpret_cast<const unsigned*>(reinterpret_cast<const unsigned char*>(p.ws + OFF_RB) + idx);
;               const float k = 1.f / 255.f;
;               st4(MERGED + idx, pack4((float)(g & 255u) * k * a[0], (float)((g >> 8) & 255u) * k * a[1], (float)((g >> 16) & 255u) * k * a[2], (float)(g >> 24) * k * a[3]));
;             } else {
;               f32x4 x = *reinterpret_cast<const f32x4*>(p.out + idx);
;               x = x * ALPHA + a;
;               *reinterpret_cast<f32x4*>(p.out + idx) = x;
;             }
;           }
;       }
;   }
.Llz_plain:
	v_lshl_add_u32 v140, s10, 8, v21
	s_lshl_b32 s10, s11, 10
	v_readlane_b32 s14, v249, 4
	v_readlane_b32 s15, v249, 5
	v_readlane_b32 s13, v251, 6
	s_mov_b32 s16, 0x3fd744fd
	v_and_b32_e32 v147, 63, v153
	v_and_b32_e32 v148, 15, v153
	v_lshrrev_b32_e32 v149, 3, v147
	s_add_i32 s10, s10, s13
	s_add_i32 s12, s12, -1
	s_lshl_b32 s12, s12, 12
	v_sub_u32_e32 v140, v140, v148
	v_add_u32_e32 v140, v140, v149
	v_and_b32_e32 v146, 7, v153
	v_lshlrev_b32_e32 v141, 3, v140
	v_lshl_add_u32 v146, v146, 4, s10
	v_lshl_add_u32 v140, v140, 12, v146
	v_lshrrev_b32_e32 v144, 6, v153
	v_lshlrev_b32_e32 v144, 11, v144
	v_add_u32_e32 v144, 0x20000, v144
	v_lshl_add_u32 v145, v149, 6, v144
	v_lshl_add_u32 v144, v148, 6, v144
	v_bfe_u32 v148, v153, 4, 2
	v_lshl_add_u32 v144, v148, 4, v144
	v_bfe_u32 v148, v153, 2, 1
	v_lshl_add_u32 v145, v148, 10, v145
	v_and_b32_e32 v148, 3, v153
	v_lshl_add_u32 v145, v148, 4, v145
	v_readlane_b32 s72, v249, 38
	v_readlane_b32 s73, v249, 39
	v_readlane_b32 s74, v249, 40
	v_readlane_b32 s75, v249, 41
	v_readlane_b32 s76, v249, 0
	v_readlane_b32 s77, v249, 1
	s_add_u32 s72, s72, s12
	s_addc_u32 s73, s73, 0
	s_add_u32 s74, s74, s12
	s_addc_u32 s75, s75, 0
	s_add_u32 s76, s76, 0x2b234000
	s_addc_u32 s77, s77, 0
	s_add_u32 s56, s14, 0x0
	s_addc_u32 s57, s15, 0
	s_add_u32 s78, s14, 0x8000
	s_addc_u32 s79, s15, 0
	s_add_u32 s58, s14, 0x10000
	s_addc_u32 s59, s15, 0
	s_add_u32 s80, s14, 0x18000
	s_addc_u32 s81, s15, 0
	s_add_u32 s60, s14, 0x20000
	s_addc_u32 s61, s15, 0
	s_add_u32 s82, s14, 0x28000
	s_addc_u32 s83, s15, 0
	s_add_u32 s62, s14, 0x30000
	s_addc_u32 s63, s15, 0
	s_add_u32 s84, s14, 0x38000
	s_addc_u32 s85, s15, 0
	s_add_u32 s64, s14, 0x80000
	s_addc_u32 s65, s15, 0
	s_add_u32 s86, s14, 0x88000
	s_addc_u32 s87, s15, 0
	s_add_u32 s66, s14, 0x90000
	s_addc_u32 s67, s15, 0
	s_add_u32 s88, s14, 0x98000
	s_addc_u32 s89, s15, 0
	s_add_u32 s68, s14, 0xa0000
	s_addc_u32 s69, s15, 0
	s_add_u32 s90, s14, 0xa8000
	s_addc_u32 s91, s15, 0
	s_add_u32 s70, s14, 0xb0000
	s_addc_u32 s71, s15, 0
	s_add_u32 s92, s14, 0xb8000
	s_addc_u32 s93, s15, 0
	s_nop 1
	global_load_dwordx4 v[204:207], v140, s[56:57]
	global_load_dwordx4 v[208:211], v140, s[78:79]
	global_load_dwordx4 v[212:215], v140, s[56:57] offset:512
	global_load_dwordx4 v[216:219], v140, s[78:79] offset:512
	global_load_dwordx4 v[220:223], v140, s[58:59]
	global_load_dwordx4 v[224:227], v140, s[80:81]
	global_load_dwordx4 v[228:231], v140, s[58:59] offset:512
	global_load_dwordx4 v[232:235], v140, s[80:81] offset:512
	global_load_dwordx4 v[236:239], v140, s[60:61]
	global_load_dwordx4 v[240:243], v140, s[82:83]
	global_load_dwordx4 v[244:247], v140, s[60:61] offset:512
	ds_write_b128 v144, v[130:133]
	ds_write_b128 v144, v[126:129] offset:1024
	ds_read_b128 v[186:189], v145
	ds_read_b128 v[190:193], v145 offset:512
	ds_write_b128 v144, v[122:125]
	ds_write_b128 v144, v[118:121] offset:1024
	ds_read_b128 v[194:197], v145
	ds_read_b128 v[198:201], v145 offset:512
	s_waitcnt lgkmcnt(4)
	s_waitcnt vmcnt(10)
	v_pk_fma_f32 v[186:187], v[204:205], s[16:17], v[186:187] op_sel_hi:[1,0,1]
	v_pk_fma_f32 v[188:189], v[206:207], s[16:17], v[188:189] op_sel_hi:[1,0,1]
	global_store_dwordx4 v140, v[186:189], s[56:57]
	global_load_dwordx4 v[204:207], v140, s[82:83] offset:512
	s_waitcnt vmcnt(11)
	v_pk_fma_f32 v[190:191], v[208:209], s[16:17], v[190:191] op_sel_hi:[1,0,1]
	v_pk_fma_f32 v[192:193], v[210:211], s[16:17], v[192:193] op_sel_hi:[1,0,1]
	global_store_dwordx4 v140, v[190:193], s[78:79]
	global_load_dwordx4 v[208:211], v140, s[62:63]
	ds_write_b128 v144, v[114:117]
	ds_write_b128 v144, v[110:113] offset:1024
	ds_read_b128 v[186:189], v145
	ds_read_b128 v[190:193], v145 offset:512
	s_waitcnt lgkmcnt(4)
	s_waitcnt vmcnt(12)
	v_pk_fma_f32 v[194:195], v[212:213], s[16:17], v[194:195] op_sel_hi:[1,0,1]
	v_pk_fma_f32 v[196:197], v[214:215], s[16:17], v[196:197] op_sel_hi:[1,0,1]
	global_store_dwordx4 v140, v[194:197], s[56:57] offset:512
	global_load_dwordx4 v[212:215], v140, s[84:85]
	s_waitcnt vmcnt(13)
	v_pk_fma_f32 v[198:199], v[216:217], s[16:17], v[198:199] op_sel_hi:[1,0,1]
	v_pk_fma_f32 v[200:201], v[218:219], s[16:17], v[200:201] op_sel_hi:[1,0,1]
	global_store_dwordx4 v140, v[198:201], s[78:79] offset:512
	global_load_dwordx4 v[216:219], v140, s[62:63] offset:512
	ds_write_b128 v144, v[106:109]
	ds_write_b128 v144, v[102:105] offset:1024
	ds_read_b128 v[194:197], v145
	ds_read_b128 v[198:201], v145 offset:512
	s_waitcnt lgkmcnt(4)
	s_waitcnt vmcnt(14)
	v_pk_fma_f32 v[186:187], v[220:221], s[16:17], v[186:187] op_sel_hi:[1,0,1]
	v_pk_fma_f32 v[188:189], v[222:223], s[16:17], v[188:189] op_sel_hi:[1,0,1]
	global_store_dwordx4 v140, v[186:189], s[58:59]
	global_load_dwordx4 v[220:223], v140, s[84:85] offset:512
	s_waitcnt vmcnt(15)
	v_pk_fma_f32 v[190:191], v[224:225], s[16:17], v[190:191] op_sel_hi:[1,0,1]
	v_pk_fma_f32 v[192:193], v[226:227], s[16:17], v[192:193] op_sel_hi:[1,0,1]
	global_store_dwordx4 v140, v[190:193], s[80:81]
	global_load_dwordx4 v[224:227], v140, s[64:65]
	ds_write_b128 v144, v[98:101]
	ds_write_b128 v144, v[94:97] offset:1024
	ds_read_b128 v[186:189], v145
	ds_read_b128 v[190:193], v145 offset:512
	s_waitcnt lgkmcnt(4)
	s_waitcnt vmcnt(16)
	v_pk_fma_f32 v[194:195], v[228:229], s[16:17], v[194:195] op_sel_hi:[1,0,1]
	v_pk_fma_f32 v[196:197], v[230:231], s[16:17], v[196:197] op_sel_hi:[1,0,1]
	global_store_dwordx4 v140, v[194:197], s[58:59] offset:512
	global_load_dwordx4 v[228:231], v140, s[86:87]
	s_waitcnt vmcnt(17)
; DI bf16x4 pack4(float a, float b, float c, float d) { u32x2v u; u.x = pk2(a, b); u.y = pk2(c, d); return __builtin_bit_cast(bf16x4, u); }
;   DI void operator()(const f32x4 (&acc)[2][2][4][2], const pg8::Unit& u, int wr, int wc, int fr, int fq) const {
;     bf16_t* MERGED = (reinterpret_cast<bf16_t*>(p.ws + OFF_GA));
; #pragma unroll
;     for (int ai = 0; ai < 2; ++ai)
; #pragma unroll
;       for (int m = 0; m < 4; ++m) {
;         const int row = u.pm * 256 + 128 * ai + 64 * wr + 16 * m + fr;
; #pragma unroll
;         for (int bj = 0; bj < 2; ++bj)
; #pragma unroll
;           for (int n = 0; n < 2; ++n) {
;             const size_t idx = (size_t)row * 1024 + u.pn * 256 + 128 * bj + 32 * wc + 16 * n + 4 * fq;
;             const f32x4 a = acc[ai][bj][m][n];
;             if (MODE == 0) {
;               const unsigned g = *reinterpret_cast<const unsigned*>(reinterpret_cast<const unsigned char*>(p.ws + OFF_RB) + idx);
;               const float k = 1.f / 255.f;
;               st4(MERGED + idx, pack4((float)(g & 255u) * k * a[0], (float)((g >> 8) & 255u) * k * a[1], (float)((g >> 16) & 255u) * k * a[2], (float)(g >> 24) * k * a[3]));
;             } else {
;               f32x4 x = *reinterpret_cast<const f32x4*>(p.out + idx);
;               x = x * ALPHA + a;
;               *reinterpret_cast<f32x4*>(p.out + idx) = x;
;             }
;           }
;       }
;   }
	v_pk_fma_f32 v[198:199], v[232:233], s[16:17], v[198:199] op_sel_hi:[1,0,1]
	v_pk_fma_f32 v[200:201], v[234:235], s[16:17], v[200:201] op_sel_hi:[1,0,1]
	global_store_dwordx4 v140, v[198:201], s[80:81] offset:512
	global_load_dwordx4 v[232:235], v140, s[64:65] offset:512
	ds_write_b128 v144, v[90:93]
	ds_write_b128 v144, v[86:89] offset:1024
	ds_read_b128 v[194:197], v145
	ds_read_b128 v[198:201], v145 offset:512
	s_waitcnt lgkmcnt(4)
	s_waitcnt vmcnt(18)
	v_pk_fma_f32 v[186:187], v[236:237], s[16:17], v[186:187] op_sel_hi:[1,0,1]
	v_pk_fma_f32 v[188:189], v[238:239], s[16:17], v[188:189] op_sel_hi:[1,0,1]
	global_store_dwordx4 v140, v[186:189], s[60:61]
	global_load_dwordx4 v[236:239], v140, s[86:87] offset:512
	s_waitcnt vmcnt(19)
	v_pk_fma_f32 v[190:191], v[240:241], s[16:17], v[190:191] op_sel_hi:[1,0,1]
	v_pk_fma_f32 v[192:193], v[242:243], s[16:17], v[192:193] op_sel_hi:[1,0,1]
	global_store_dwordx4 v140, v[190:193], s[82:83]
	global_load_dwordx4 v[240:243], v140, s[66:67]
	ds_write_b128 v144, v[82:85]
	ds_write_b128 v144, v[78:81] offset:1024
	ds_read_b128 v[186:189], v145
	ds_read_b128 v[190:193], v145 offset:512
	s_waitcnt lgkmcnt(4)
	s_waitcnt vmcnt(20)
	v_pk_fma_f32 v[194:195], v[244:245], s[16:17], v[194:195] op_sel_hi:[1,0,1]
	v_pk_fma_f32 v[196:197], v[246:247], s[16:17], v[196:197] op_sel_hi:[1,0,1]
	global_store_dwordx4 v140, v[194:197], s[60:61] offset:512
	global_load_dwordx4 v[244:247], v140, s[88:89]
	s_waitcnt vmcnt(20)
	v_pk_fma_f32 v[198:199], v[204:205], s[16:17], v[198:199] op_sel_hi:[1,0,1]
	v_pk_fma_f32 v[200:201], v[206:207], s[16:17], v[200:201] op_sel_hi:[1,0,1]
	global_store_dwordx4 v140, v[198:201], s[82:83] offset:512
	global_load_dwordx4 v[204:207], v140, s[66:67] offset:512
	ds_write_b128 v144, v[74:77]
	ds_write_b128 v144, v[70:73] offset:1024
	ds_read_b128 v[194:197], v145
	ds_read_b128 v[198:201], v145 offset:512
	s_waitcnt lgkmcnt(4)
	s_waitcnt vmcnt(20)
	v_pk_fma_f32 v[186:187], v[208:209], s[16:17], v[186:187] op_sel_hi:[1,0,1]
	v_pk_fma_f32 v[188:189], v[210:211], s[16:17], v[188:189] op_sel_hi:[1,0,1]
	global_store_dwordx4 v140, v[186:189], s[62:63]
	global_load_dwordx4 v[208:211], v140, s[88:89] offset:512
	s_waitcnt vmcnt(20)
	v_pk_fma_f32 v[190:191], v[212:213], s[16:17], v[190:191] op_sel_hi:[1,0,1]
	v_pk_fma_f32 v[192:193], v[214:215], s[16:17], v[192:193] op_sel_hi:[1,0,1]
	global_store_dwordx4 v140, v[190:193], s[84:85]
	global_load_dwordx4 v[212:215], v140, s[68:69]
	ds_write_b128 v144, v[66:69]
	ds_write_b128 v144, v[62:65] offset:1024
	ds_read_b128 v[186:189], v145
	ds_read_b128 v[190:193], v145 offset:512
	s_waitcnt lgkmcnt(4)
	s_waitcnt vmcnt(20)
	v_pk_fma_f32 v[194:195], v[216:217], s[16:17], v[194:195] op_sel_hi:[1,0,1]
	v_pk_fma_f32 v[196:197], v[218:219], s[16:17], v[196:197] op_sel_hi:[1,0,1]
	global_store_dwordx4 v140, v[194:197], s[62:63] offset:512
	global_load_dwordx4 v[216:219], v140, s[90:91]
	s_waitcnt vmcnt(20)
	v_pk_fma_f32 v[198:199], v[220:221], s[16:17], v[198:199] op_sel_hi:[1,0,1]
	v_pk_fma_f32 v[200:201], v[222:223], s[16:17], v[200:201] op_sel_hi:[1,0,1]
	global_store_dwordx4 v140, v[198:201], s[84:85] offset:512
	global_load_dwordx4 v[220:223], v140, s[68:69] offset:512
	ds_write_b128 v144, v[58:61]
	ds_write_b128 v144, v[54:57] offset:1024
	ds_read_b128 v[194:197], v145
	ds_read_b128 v[198:201], v145 offset:512
	s_waitcnt lgkmcnt(4)
	s_waitcnt vmcnt(20)
	v_pk_fma_f32 v[186:187], v[224:225], s[16:17], v[186:187] op_sel_hi:[1,0,1]
	v_pk_fma_f32 v[188:189], v[226:227], s[16:17], v[188:189] op_sel_hi:[1,0,1]
	global_store_dwordx4 v140, v[186:189], s[64:65]
	global_load_dwordx4 v[224:227], v140, s[90:91] offset:512
	s_waitcnt vmcnt(20)
	v_pk_fma_f32 v[190:191], v[228:229], s[16:17], v[190:191] op_sel_hi:[1,0,1]
	v_pk_fma_f32 v[192:193], v[230:231], s[16:17], v[192:193] op_sel_hi:[1,0,1]
	global_store_dwordx4 v140, v[190:193], s[86:87]
	global_load_dwordx4 v[228:231], v140, s[70:71]
	ds_write_b128 v144, v[50:53]
	ds_write_b128 v144, v[46:49] offset:1024
	ds_read_b128 v[186:189], v145
	ds_read_b128 v[190:193], v145 offset:512
	s_waitcnt lgkmcnt(4)
	s_waitcnt vmcnt(20)
; DI bf16x4 pack4(float a, float b, float c, float d) { u32x2v u; u.x = pk2(a, b); u.y = pk2(c, d); return __builtin_bit_cast(bf16x4, u); }
;   DI void operator()(const f32x4 (&acc)[2][2][4][2], const pg8::Unit& u, int wr, int wc, int fr, int fq) const {
;     bf16_t* MERGED = (reinterpret_cast<bf16_t*>(p.ws + OFF_GA));
; #pragma unroll
;     for (int ai = 0; ai < 2; ++ai)
; #pragma unroll
;       for (int m = 0; m < 4; ++m) {
;         const int row = u.pm * 256 + 128 * ai + 64 * wr + 16 * m + fr;
; #pragma unroll
;         for (int bj = 0; bj < 2; ++bj)
; #pragma unroll
;           for (int n = 0; n < 2; ++n) {
;             const size_t idx = (size_t)row * 1024 + u.pn * 256 + 128 * bj + 32 * wc + 16 * n + 4 * fq;
;             const f32x4 a = acc[ai][bj][m][n];
;             if (MODE == 0) {
;               const unsigned g = *reinterpret_cast<const unsigned*>(reinterpret_cast<const unsigned char*>(p.ws + OFF_RB) + idx);
;               const float k = 1.f / 255.f;
;               st4(MERGED + idx, pack4((float)(g & 255u) * k * a[0], (float)((g >> 8) & 255u) * k * a[1], (float)((g >> 16) & 255u) * k * a[2], (float)(g >> 24) * k * a[3]));
;             } else {
;               f32x4 x = *reinterpret_cast<const f32x4*>(p.out + idx);
;               x = x * ALPHA + a;
;               *reinterpret_cast<f32x4*>(p.out + idx) = x;
;             }
;           }
;       }
;   }
	v_pk_fma_f32 v[194:195], v[232:233], s[16:17], v[194:195] op_sel_hi:[1,0,1]
	v_pk_fma_f32 v[196:197], v[234:235], s[16:17], v[196:197] op_sel_hi:[1,0,1]
	global_store_dwordx4 v140, v[194:197], s[64:65] offset:512
	global_load_dwordx4 v[232:235], v140, s[92:93]
	s_waitcnt vmcnt(20)
	v_pk_fma_f32 v[198:199], v[236:237], s[16:17], v[198:199] op_sel_hi:[1,0,1]
	v_pk_fma_f32 v[200:201], v[238:239], s[16:17], v[200:201] op_sel_hi:[1,0,1]
	global_store_dwordx4 v140, v[198:201], s[86:87] offset:512
	global_load_dwordx4 v[236:239], v140, s[70:71] offset:512
	ds_write_b128 v144, v[42:45]
	ds_write_b128 v144, v[38:41] offset:1024
	ds_read_b128 v[194:197], v145
	ds_read_b128 v[198:201], v145 offset:512
	s_waitcnt lgkmcnt(4)
	s_waitcnt vmcnt(20)
	v_pk_fma_f32 v[186:187], v[240:241], s[16:17], v[186:187] op_sel_hi:[1,0,1]
	v_pk_fma_f32 v[188:189], v[242:243], s[16:17], v[188:189] op_sel_hi:[1,0,1]
	global_store_dwordx4 v140, v[186:189], s[66:67]
	global_load_dwordx4 v[240:243], v140, s[92:93] offset:512
	s_waitcnt vmcnt(20)
	v_pk_fma_f32 v[190:191], v[244:245], s[16:17], v[190:191] op_sel_hi:[1,0,1]
	v_pk_fma_f32 v[192:193], v[246:247], s[16:17], v[192:193] op_sel_hi:[1,0,1]
	global_store_dwordx4 v140, v[190:193], s[88:89]
	ds_write_b128 v144, v[34:37]
	ds_write_b128 v144, v[30:33] offset:1024
	ds_read_b128 v[186:189], v145
	ds_read_b128 v[190:193], v145 offset:512
	s_waitcnt lgkmcnt(4)
	s_waitcnt vmcnt(19)
	v_pk_fma_f32 v[194:195], v[204:205], s[16:17], v[194:195] op_sel_hi:[1,0,1]
	v_pk_fma_f32 v[196:197], v[206:207], s[16:17], v[196:197] op_sel_hi:[1,0,1]
	global_store_dwordx4 v140, v[194:197], s[66:67] offset:512
	s_waitcnt vmcnt(18)
	v_pk_fma_f32 v[198:199], v[208:209], s[16:17], v[198:199] op_sel_hi:[1,0,1]
	v_pk_fma_f32 v[200:201], v[210:211], s[16:17], v[200:201] op_sel_hi:[1,0,1]
	global_store_dwordx4 v140, v[198:201], s[88:89] offset:512
	ds_write_b128 v144, v[26:29]
	ds_write_b128 v144, v[22:25] offset:1024
	ds_read_b128 v[194:197], v145
	ds_read_b128 v[198:201], v145 offset:512
	s_waitcnt lgkmcnt(4)
	s_waitcnt vmcnt(17)
	v_pk_fma_f32 v[186:187], v[212:213], s[16:17], v[186:187] op_sel_hi:[1,0,1]
	v_pk_fma_f32 v[188:189], v[214:215], s[16:17], v[188:189] op_sel_hi:[1,0,1]
	global_store_dwordx4 v140, v[186:189], s[68:69]
	s_waitcnt vmcnt(16)
	v_pk_fma_f32 v[190:191], v[216:217], s[16:17], v[190:191] op_sel_hi:[1,0,1]
	v_pk_fma_f32 v[192:193], v[218:219], s[16:17], v[192:193] op_sel_hi:[1,0,1]
	global_store_dwordx4 v140, v[190:193], s[90:91]
	ds_write_b128 v144, v[12:15]
	ds_write_b128 v144, v[8:11] offset:1024
	ds_read_b128 v[186:189], v145
	ds_read_b128 v[190:193], v145 offset:512
	s_waitcnt lgkmcnt(4)
	s_waitcnt vmcnt(15)
	v_pk_fma_f32 v[194:195], v[220:221], s[16:17], v[194:195] op_sel_hi:[1,0,1]
	v_pk_fma_f32 v[196:197], v[222:223], s[16:17], v[196:197] op_sel_hi:[1,0,1]
	global_store_dwordx4 v140, v[194:197], s[68:69] offset:512
	s_waitcnt vmcnt(14)
	v_pk_fma_f32 v[198:199], v[224:225], s[16:17], v[198:199] op_sel_hi:[1,0,1]
	v_pk_fma_f32 v[200:201], v[226:227], s[16:17], v[200:201] op_sel_hi:[1,0,1]
	global_store_dwordx4 v140, v[198:201], s[90:91] offset:512
	ds_write_b128 v144, v[4:7]
	ds_write_b128 v144, v[0:3] offset:1024
	ds_read_b128 v[194:197], v145
	ds_read_b128 v[198:201], v145 offset:512
	s_waitcnt lgkmcnt(4)
	s_waitcnt vmcnt(13)
	v_pk_fma_f32 v[186:187], v[228:229], s[16:17], v[186:187] op_sel_hi:[1,0,1]
	v_pk_fma_f32 v[188:189], v[230:231], s[16:17], v[188:189] op_sel_hi:[1,0,1]
	global_store_dwordx4 v140, v[186:189], s[70:71]
	s_waitcnt vmcnt(12)
	v_pk_fma_f32 v[190:191], v[232:233], s[16:17], v[190:191] op_sel_hi:[1,0,1]
	v_pk_fma_f32 v[192:193], v[234:235], s[16:17], v[192:193] op_sel_hi:[1,0,1]
	global_store_dwordx4 v140, v[190:193], s[92:93]
	s_waitcnt lgkmcnt(0)
	s_waitcnt vmcnt(11)
	v_pk_fma_f32 v[194:195], v[236:237], s[16:17], v[194:195] op_sel_hi:[1,0,1]
	v_pk_fma_f32 v[196:197], v[238:239], s[16:17], v[196:197] op_sel_hi:[1,0,1]
	global_store_dwordx4 v140, v[194:197], s[70:71] offset:512
	s_waitcnt vmcnt(10)
	v_pk_fma_f32 v[198:199], v[240:241], s[16:17], v[198:199] op_sel_hi:[1,0,1]
	v_pk_fma_f32 v[200:201], v[242:243], s[16:17], v[200:201] op_sel_hi:[1,0,1]
	global_store_dwordx4 v140, v[198:201], s[92:93] offset:512
